# DIFF attention: first P.V transposed-read group issued above the K/V ds_write block, first P.V wait counted lgkmcnt(4)
# speedup vs baseline: 1.0069x; 1.0069x over previous
; #define SBAR() __builtin_amdgcn_sched_barrier(0)
; template <int D0> __device__ __forceinline__ void pv_one(f32x16& od, int vb, bf16x8 pa0, bf16x8 pa1, bf16x8 pa2, bf16x8 pa3) {
;   const s16x4 l0 = tr_read<v_rd_off(D0, 0, 0)>(vb), h0 = tr_read<v_rd_off(D0, 0, 1)>(vb), l1 = tr_read<v_rd_off(D0, 1, 0)>(vb), h1 = tr_read<v_rd_off(D0, 1, 1)>(vb);
;   const s16x4 l2 = tr_read<v_rd_off(D0, 2, 0)>(vb), h2 = tr_read<v_rd_off(D0, 2, 1)>(vb), l3 = tr_read<v_rd_off(D0, 3, 0)>(vb), h3 = tr_read<v_rd_off(D0, 3, 1)>(vb);
;   asm volatile("s_waitcnt lgkmcnt(0)" ::: "memory"); SBAR();
.LBB0_316:
	s_lshl_b32 s10, s35, 14
	s_add_i32 s8, s10, 0
	v_add_u32_e32 v102, s8, v183
	ds_read_b128 v[98:101], v102 offset:49152
	v_add_u32_e32 v103, s8, v197
	ds_read_b128 v[200:203], v102 offset:57344
	ds_read_b128 v[222:225], v103 offset:49152
	ds_read_b128 v[226:229], v103 offset:57344
	v_add_u32_e32 v204, s8, v196
	v_exp_f32_e32 v205, v85
	v_exp_f32_e32 v97, v97
	s_waitcnt lgkmcnt(3)
	v_mfma_f32_32x32x16_bf16 v[114:129], v[98:101], v[142:145], v[66:81]
	s_waitcnt lgkmcnt(2)
	v_mfma_f32_32x32x16_bf16 v[98:113], v[200:203], v[142:145], v[66:81]
	ds_read_b128 v[200:203], v204 offset:49152
	ds_read_b128 v[230:233], v204 offset:57344
	v_add_u32_e32 v204, s8, v198
	s_waitcnt lgkmcnt(3)
	v_mfma_f32_32x32x16_bf16 v[114:129], v[222:225], v[138:141], v[114:129]
	s_waitcnt lgkmcnt(2)
	v_mfma_f32_32x32x16_bf16 v[98:113], v[226:229], v[138:141], v[98:113]
	ds_read_b128 v[222:225], v204 offset:49152
	ds_read_b128 v[226:229], v204 offset:57344
	v_exp_f32_e32 v204, v84
	s_waitcnt lgkmcnt(3)
	v_mfma_f32_32x32x16_bf16 v[114:129], v[200:203], v[134:137], v[114:129]
	v_exp_f32_e32 v202, v82
	v_add_f32_e32 v82, 0, v219
	v_add_f32_e32 v82, v221, v82
	v_add_f32_e32 v82, v217, v82
	v_add_f32_e32 v82, v220, v82
	v_add_f32_e32 v82, v215, v82
	v_add_f32_e32 v82, v218, v82
	v_add_f32_e32 v82, v214, v82
	v_add_f32_e32 v82, v216, v82
	v_add_f32_e32 v82, v211, v82
	v_add_f32_e32 v82, v213, v82
	v_add_f32_e32 v82, v209, v82
	v_add_f32_e32 v82, v212, v82
	s_waitcnt lgkmcnt(2)
	v_mfma_f32_32x32x16_bf16 v[98:113], v[230:233], v[134:137], v[98:113]
	v_add_f32_e32 v82, v207, v82
	v_exp_f32_e32 v203, v83
	v_add_f32_e32 v82, v210, v82
	v_add_f32_e32 v82, v206, v82
	v_add_f32_e32 v82, v208, v82
	v_add_f32_e32 v82, v202, v82
	v_add_f32_e32 v82, v203, v82
	s_waitcnt lgkmcnt(1)
	v_mfma_f32_32x32x16_bf16 v[114:129], v[222:225], v[130:133], v[114:129]
	v_exp_f32_e32 v222, v86
	v_exp_f32_e32 v223, v87
	v_exp_f32_e32 v224, v88
	v_add_f32_e32 v82, v204, v82
	v_exp_f32_e32 v225, v89
	v_add_f32_e32 v82, v205, v82
	v_add_f32_e32 v82, v222, v82
	s_waitcnt lgkmcnt(0)
	v_mfma_f32_32x32x16_bf16 v[98:113], v[226:229], v[130:133], v[98:113]
	v_exp_f32_e32 v226, v90
	v_exp_f32_e32 v227, v91
	v_add_f32_e32 v82, v223, v82
	v_exp_f32_e32 v228, v92
	v_add_f32_e32 v82, v224, v82
	v_exp_f32_e32 v229, v93
	v_add_f32_e32 v82, v225, v82
	v_exp_f32_e32 v230, v94
	v_add_f32_e32 v82, v226, v82
	v_exp_f32_e32 v231, v95
	v_add_f32_e32 v82, v227, v82
	v_exp_f32_e32 v232, v96
	v_add_f32_e32 v82, v228, v82
	v_add_f32_e32 v82, v229, v82
	v_add_f32_e32 v82, v230, v82
	v_add_f32_e32 v82, v231, v82
	v_add_f32_e32 v82, v232, v82
	v_add_f32_e32 v200, v97, v82
	v_mov_b32_e32 v201, v200
	v_cvt_pk_bf16_f32 v82, v219, v221
	v_cvt_pk_bf16_f32 v83, v217, v220
	v_cvt_pk_bf16_f32 v84, v215, v218
	s_nop 1
	v_permlane32_swap_b32_e32 v200, v201
	v_cvt_pk_bf16_f32 v85, v214, v216
	v_permlane32_swap_b32_e32 v82, v84
	v_cvt_pk_bf16_f32 v86, v211, v213
	v_cvt_pk_bf16_f32 v87, v209, v212
	v_cvt_pk_bf16_f32 v88, v207, v210
	v_cvt_pk_bf16_f32 v89, v206, v208
	v_cvt_pk_bf16_f32 v90, v202, v203
	v_cvt_pk_bf16_f32 v91, v204, v205
	v_cvt_pk_bf16_f32 v92, v222, v223
	v_cvt_pk_bf16_f32 v93, v224, v225
	v_cvt_pk_bf16_f32 v94, v226, v227
	v_cvt_pk_bf16_f32 v95, v228, v229
	v_cvt_pk_bf16_f32 v96, v230, v231
	v_cvt_pk_bf16_f32 v97, v232, v97
	v_permlane32_swap_b32_e32 v83, v85
	v_permlane32_swap_b32_e32 v86, v88
	v_permlane32_swap_b32_e32 v87, v89
	v_permlane32_swap_b32_e32 v90, v92
	v_permlane32_swap_b32_e32 v91, v93
	v_permlane32_swap_b32_e32 v94, v96
	v_permlane32_swap_b32_e32 v95, v97
	v_lshl_add_u32 v218, s9, 14, v181
	ds_read_b64_tr_b16 v[202:203], v218 offset:0
	ds_read_b64_tr_b16 v[204:205], v218 offset:0x800
	ds_read_b64_tr_b16 v[206:207], v218 offset:0x1000
	ds_read_b64_tr_b16 v[208:209], v218 offset:0x1800
	ds_read_b64_tr_b16 v[210:211], v218 offset:0x2000
	ds_read_b64_tr_b16 v[212:213], v218 offset:0x2800
	ds_read_b64_tr_b16 v[214:215], v218 offset:0x3000
	ds_read_b64_tr_b16 v[216:217], v218 offset:0x3800
	s_lshl_b32 s13, s12, 14
	s_add_i32 s11, s13, 0
	v_add_u32_e32 v222, s11, v192
	s_waitcnt vmcnt(0)
	s_waitcnt vmcnt(3)
; #define SBAR() __builtin_amdgcn_sched_barrier(0)
; template <bool FIRST> __device__ __forceinline__ void partialSM_ps(f32x16& p0, f32x16& p1, float& m_reg, float& alpha, f32x16& negm) {
;   float pmax = p0[0];
; #pragma unroll
;   for (int r = 1; r < 16; ++r) pmax = fmaxf(pmax, p0[r]);
; #pragma unroll
;   for (int r = 0; r < 16; ++r) pmax = fmaxf(pmax, p1[r]);
;   { auto rr = __builtin_amdgcn_permlane32_swap(__float_as_uint(pmax), __float_as_uint(pmax), false, false);
;     pmax = fmaxf(__uint_as_float(rr[0]), __uint_as_float(rr[1])); }
;   alpha = 1.f;
;   if (FIRST || !__builtin_expect(__all(pmax <= THRL), 1)) {
; template <int D0> __device__ __forceinline__ void pv_one(f32x16& od, int vb, bf16x8 pa0, bf16x8 pa1, bf16x8 pa2, bf16x8 pa3) {
;   const s16x4 l0 = tr_read<v_rd_off(D0, 0, 0)>(vb), h0 = tr_read<v_rd_off(D0, 0, 1)>(vb), l1 = tr_read<v_rd_off(D0, 1, 0)>(vb), h1 = tr_read<v_rd_off(D0, 1, 1)>(vb);
;   const s16x4 l2 = tr_read<v_rd_off(D0, 2, 0)>(vb), h2 = tr_read<v_rd_off(D0, 2, 1)>(vb), l3 = tr_read<v_rd_off(D0, 3, 0)>(vb), h3 = tr_read<v_rd_off(D0, 3, 1)>(vb);
;   asm volatile("s_waitcnt lgkmcnt(0)" ::: "memory"); SBAR();
;     ...
;   od = __builtin_amdgcn_mfma_f32_32x32x16_bf16(pa0, PK(l0, h0), od, 0, 0, 0);
;   od = __builtin_amdgcn_mfma_f32_32x32x16_bf16(pa1, PK(l1, h1), od, 0, 0, 0);
;   od = __builtin_amdgcn_mfma_f32_32x32x16_bf16(pa2, PK(l2, h2), od, 0, 0, 0);
;   od = __builtin_amdgcn_mfma_f32_32x32x16_bf16(pa3, PK(l3, h3), od, 0, 0, 0);
;     ...
; }
; __device__ __forceinline__ void pv_d0(f32x16* o, int vb, bf16x8 pa0, bf16x8 pa1, bf16x8 pa2, bf16x8 pa3) {
;   pv_one<0>(o[0], vb, pa0, pa1, pa2, pa3); pv_one<1>(o[1], vb, pa0, pa1, pa2, pa3); pv_one<2>(o[2], vb, pa0, pa1, pa2, pa3); pv_one<3>(o[3], vb, pa0, pa1, pa2, pa3);
; }
	ds_write_b128 v222, v[146:149]
	v_add_u32_e32 v146, s11, v193
	s_waitcnt vmcnt(1)
	ds_write_b128 v146, v[150:153]
	v_add_u32_e32 v146, s11, v194
	s_mov_b32 s8, 0xfffa0000
	s_waitcnt vmcnt(1)
	ds_write_b128 v146, v[154:157] offset:49152
	s_waitcnt vmcnt(0)
	ds_write_b128 v146, v[158:161] offset:57344
	v_add_co_u32_e32 v146, vcc, s8, v166
	s_mov_b32 s8, 0xfffc0000
	s_nop 0
	v_addc_co_u32_e32 v147, vcc, -1, v167, vcc
	v_add_co_u32_e32 v150, vcc, s8, v166
	s_mov_b32 s8, 0xfb7a0000
	s_nop 0
	v_addc_co_u32_e32 v151, vcc, -1, v167, vcc
	v_add_co_u32_e32 v154, vcc, s8, v166
	s_mov_b32 s8, 0xfb7c0000
	s_nop 0
	v_addc_co_u32_e32 v155, vcc, -1, v167, vcc
	v_add_co_u32_e32 v158, vcc, s8, v166
	global_load_dwordx4 v[146:149], v[146:147], off
	s_nop 0
	global_load_dwordx4 v[150:153], v[150:151], off
	v_addc_co_u32_e32 v159, vcc, -1, v167, vcc
	global_load_dwordx4 v[154:157], v[154:155], off
	s_nop 0
	global_load_dwordx4 v[158:161], v[158:159], off
	s_waitcnt lgkmcnt(4)
	s_nop 0
	v_mfma_f32_32x32x16_bf16 v[2:17], v[82:85], v[202:205], v[2:17]
	ds_read_b64_tr_b16 v[202:203], v218 offset:0x200
	ds_read_b64_tr_b16 v[204:205], v218 offset:0xa00
	v_mfma_f32_32x32x16_bf16 v[2:17], v[86:89], v[206:209], v[2:17]
	ds_read_b64_tr_b16 v[206:207], v218 offset:0x1200
	ds_read_b64_tr_b16 v[208:209], v218 offset:0x1a00
	v_mfma_f32_32x32x16_bf16 v[2:17], v[90:93], v[210:213], v[2:17]
	ds_read_b64_tr_b16 v[210:211], v218 offset:0x2200
	ds_read_b64_tr_b16 v[212:213], v218 offset:0x2a00
	v_mfma_f32_32x32x16_bf16 v[2:17], v[94:97], v[214:217], v[2:17]
	ds_read_b64_tr_b16 v[214:215], v218 offset:0x3200
	ds_read_b64_tr_b16 v[216:217], v218 offset:0x3a00
	s_waitcnt lgkmcnt(0)
	v_mfma_f32_32x32x16_bf16 v[50:65], v[82:85], v[202:205], v[50:65]
	ds_read_b64_tr_b16 v[202:203], v218 offset:0x400
	ds_read_b64_tr_b16 v[204:205], v218 offset:0xc00
	v_mfma_f32_32x32x16_bf16 v[50:65], v[86:89], v[206:209], v[50:65]
	ds_read_b64_tr_b16 v[206:207], v218 offset:0x1400
	ds_read_b64_tr_b16 v[208:209], v218 offset:0x1c00
	v_mfma_f32_32x32x16_bf16 v[50:65], v[90:93], v[210:213], v[50:65]
	ds_read_b64_tr_b16 v[210:211], v218 offset:0x2400
	ds_read_b64_tr_b16 v[212:213], v218 offset:0x2c00
	v_mfma_f32_32x32x16_bf16 v[50:65], v[94:97], v[214:217], v[50:65]
	ds_read_b64_tr_b16 v[214:215], v218 offset:0x3400
	ds_read_b64_tr_b16 v[216:217], v218 offset:0x3c00
	s_waitcnt lgkmcnt(0)
	v_mfma_f32_32x32x16_bf16 v[34:49], v[82:85], v[202:205], v[34:49]
	ds_read_b64_tr_b16 v[202:203], v218 offset:0x600
	ds_read_b64_tr_b16 v[204:205], v218 offset:0xe00
	v_mfma_f32_32x32x16_bf16 v[34:49], v[86:89], v[206:209], v[34:49]
	ds_read_b64_tr_b16 v[206:207], v218 offset:0x1600
	ds_read_b64_tr_b16 v[208:209], v218 offset:0x1e00
	v_mfma_f32_32x32x16_bf16 v[34:49], v[90:93], v[210:213], v[34:49]
	ds_read_b64_tr_b16 v[210:211], v218 offset:0x2600
	ds_read_b64_tr_b16 v[212:213], v218 offset:0x2e00
	v_mfma_f32_32x32x16_bf16 v[34:49], v[94:97], v[214:217], v[34:49]
	ds_read_b64_tr_b16 v[214:215], v218 offset:0x3600
	ds_read_b64_tr_b16 v[216:217], v218 offset:0x3e00
	s_waitcnt lgkmcnt(0)
	v_mfma_f32_32x32x16_bf16 v[18:33], v[82:85], v[202:205], v[18:33]
	v_max_f32_e32 v82, v115, v115
	v_max_f32_e32 v83, v114, v114
	v_max_f32_e32 v82, v83, v82
	v_max3_f32 v82, v82, v116, v117
	v_max3_f32 v82, v82, v118, v119
	v_max3_f32 v82, v82, v120, v121
	v_max3_f32 v82, v82, v122, v123
	v_mfma_f32_32x32x16_bf16 v[18:33], v[86:89], v[206:209], v[18:33]
	v_max3_f32 v82, v82, v124, v125
	v_max3_f32 v82, v82, v126, v127
	v_max3_f32 v82, v82, v128, v129
	v_max3_f32 v82, v82, v98, v99
	v_max3_f32 v82, v82, v100, v101
	v_max3_f32 v82, v82, v102, v103
	v_max3_f32 v82, v82, v104, v105
	v_mfma_f32_32x32x16_bf16 v[18:33], v[90:93], v[210:213], v[18:33]
	v_max3_f32 v82, v82, v106, v107
	v_max3_f32 v82, v82, v108, v109
	v_max3_f32 v82, v82, v110, v111
	v_max3_f32 v82, v82, v112, v113
	v_mov_b32_e32 v83, v82
	s_nop 1
	v_permlane32_swap_b32_e32 v82, v83
	v_mfma_f32_32x32x16_bf16 v[18:33], v[94:97], v[214:217], v[18:33]
	v_max_f32_e32 v83, v83, v83
	v_max_f32_e32 v82, v82, v82
	v_max_f32_e32 v82, v82, v83
	v_cmp_ge_f32_e32 vcc, s0, v82
	s_cmp_eq_u64 vcc, exec
	s_cbranch_scc0 .LBB0_331
	v_mov_b32_e32 v203, 1.0

; template <int DQK, int KW, int QSP> __device__ __forceinline__ void qkt(f32x16& p0, f32x16& p1, const char* Ks, const int (&kb)[4], const bf16x8* qr, const char* qsp, const f32x16& cinit) {
;   p0 = cinit; p1 = cinit;
;   constexpr int N = DQK / 16;
;     ...
;   bf16x8 f0[2], f1[2];
;   f0[0] = KRD(0, 1); f1[0] = KRD(0, 0);
; #pragma unroll
;   for (int d0 = 0; d0 < N; ++d0) {
;     if (d0 + 1 < N) { f0[(d0 + 1) & 1] = KRD(d0 + 1, 1); f1[(d0 + 1) & 1] = KRD(d0 + 1, 0); }
;     __builtin_amdgcn_sched_barrier(0x406);
;     bf16x8 qf;
;     if constexpr (QSP > 0) { if (d0 >= N - QSP) qf = *reinterpret_cast<const bf16x8*>(qsp + (d0 - (N - QSP)) * 1024); else qf = qr[d0]; } else qf = qr[d0];
;     p0 = __builtin_amdgcn_mfma_f32_32x32x16_bf16(f0[d0 & 1], qf, p0, 0, 0, 0);
;     p1 = __builtin_amdgcn_mfma_f32_32x32x16_bf16(f1[d0 & 1], qf, p1, 0, 0, 0);
;     __builtin_amdgcn_sched_barrier(0x406); }
.LBB0_322:
	s_add_i32 s8, s12, 1
	s_cmp_lg_u32 s12, 2
	s_cselect_b32 s35, s8, 0
	v_exp_f32_e32 v202, v114
	v_exp_f32_e32 v220, v115
	v_exp_f32_e32 v221, v116
	v_exp_f32_e32 v222, v117
	v_exp_f32_e32 v223, v118
	v_exp_f32_e32 v224, v119
	v_exp_f32_e32 v225, v120
	v_exp_f32_e32 v226, v121
	v_exp_f32_e32 v227, v122
	v_exp_f32_e32 v228, v123
	v_exp_f32_e32 v229, v124
	v_exp_f32_e32 v230, v125
	v_exp_f32_e32 v231, v126
	v_exp_f32_e32 v232, v127
	v_exp_f32_e32 v233, v128
	v_exp_f32_e32 v234, v129
	v_add_u32_e32 v86, s11, v183
	ds_read_b128 v[82:85], v86 offset:49152
	v_add_u32_e32 v87, s11, v197
	ds_read_b128 v[204:207], v86 offset:57344
	ds_read_b128 v[208:211], v87 offset:49152
	ds_read_b128 v[212:215], v87 offset:57344
	v_add_u32_e32 v216, s11, v196
	v_exp_f32_e32 v235, v112
	v_exp_f32_e32 v113, v113
	s_waitcnt lgkmcnt(3)
	v_mfma_f32_32x32x16_bf16 v[114:129], v[82:85], v[142:145], v[66:81]
	s_waitcnt lgkmcnt(2)
	v_mfma_f32_32x32x16_bf16 v[82:97], v[204:207], v[142:145], v[66:81]
	ds_read_b128 v[204:207], v216 offset:49152
	ds_read_b128 v[216:219], v216 offset:57344
	s_waitcnt lgkmcnt(3)
	v_mfma_f32_32x32x16_bf16 v[114:129], v[208:211], v[138:141], v[114:129]
	s_waitcnt lgkmcnt(2)
	v_mfma_f32_32x32x16_bf16 v[82:97], v[212:215], v[138:141], v[82:97]
	v_add_u32_e32 v212, s11, v198
	ds_read_b128 v[208:211], v212 offset:49152
	ds_read_b128 v[212:215], v212 offset:57344
	s_waitcnt lgkmcnt(3)
	v_mfma_f32_32x32x16_bf16 v[114:129], v[204:207], v[134:137], v[114:129]
	v_exp_f32_e32 v206, v98
	v_add_f32_e32 v98, 0, v202
	v_add_f32_e32 v98, v220, v98
	v_add_f32_e32 v98, v221, v98
	v_add_f32_e32 v98, v222, v98
	v_add_f32_e32 v98, v223, v98
	v_add_f32_e32 v98, v224, v98
	v_add_f32_e32 v98, v225, v98
	v_add_f32_e32 v98, v226, v98
	v_add_f32_e32 v98, v227, v98
	v_add_f32_e32 v98, v228, v98
	s_waitcnt lgkmcnt(2)
	v_mfma_f32_32x32x16_bf16 v[82:97], v[216:219], v[134:137], v[82:97]
	v_add_f32_e32 v98, v229, v98
	v_add_f32_e32 v98, v230, v98
	v_add_f32_e32 v98, v231, v98
	v_exp_f32_e32 v207, v99
	v_add_f32_e32 v98, v232, v98
	v_add_f32_e32 v98, v233, v98
	v_add_f32_e32 v98, v234, v98
	s_waitcnt lgkmcnt(1)
	v_mfma_f32_32x32x16_bf16 v[114:129], v[208:211], v[130:133], v[114:129]
	v_exp_f32_e32 v208, v100
	v_exp_f32_e32 v209, v101
	v_exp_f32_e32 v210, v102
	v_add_f32_e32 v98, v206, v98
	v_exp_f32_e32 v211, v103
	v_add_f32_e32 v98, v207, v98
	v_add_f32_e32 v98, v208, v98
	s_waitcnt lgkmcnt(0)
	v_mfma_f32_32x32x16_bf16 v[82:97], v[212:215], v[130:133], v[82:97]
	v_exp_f32_e32 v212, v104
	v_exp_f32_e32 v213, v105
	v_add_f32_e32 v98, v209, v98
	v_exp_f32_e32 v214, v106
	v_add_f32_e32 v98, v210, v98
	v_exp_f32_e32 v215, v107
	v_add_f32_e32 v98, v211, v98
	v_exp_f32_e32 v216, v108
	v_add_f32_e32 v98, v212, v98
	v_exp_f32_e32 v217, v109
	v_add_f32_e32 v98, v213, v98
	v_exp_f32_e32 v218, v110
	v_add_f32_e32 v98, v214, v98
	v_exp_f32_e32 v219, v111
	v_add_f32_e32 v98, v215, v98
	v_add_f32_e32 v98, v216, v98
	v_add_f32_e32 v98, v217, v98
	v_add_f32_e32 v98, v218, v98
	v_add_f32_e32 v98, v219, v98
	v_add_f32_e32 v98, v235, v98
	v_add_f32_e32 v204, v113, v98
	v_mov_b32_e32 v205, v204
	v_cvt_pk_bf16_f32 v98, v202, v220
	v_cvt_pk_bf16_f32 v99, v221, v222
	v_cvt_pk_bf16_f32 v100, v223, v224
	v_cvt_pk_bf16_f32 v101, v225, v226
	v_cvt_pk_bf16_f32 v102, v227, v228
	v_cvt_pk_bf16_f32 v103, v229, v230
	v_cvt_pk_bf16_f32 v104, v231, v232
	v_cvt_pk_bf16_f32 v105, v233, v234
	v_cvt_pk_bf16_f32 v106, v206, v207
	v_cvt_pk_bf16_f32 v107, v208, v209
	v_cvt_pk_bf16_f32 v108, v210, v211
	v_cvt_pk_bf16_f32 v109, v212, v213
	v_cvt_pk_bf16_f32 v110, v214, v215
	v_cvt_pk_bf16_f32 v111, v216, v217
	v_cvt_pk_bf16_f32 v112, v218, v219
	v_cvt_pk_bf16_f32 v113, v235, v113
	s_nop 1
	v_permlane32_swap_b32_e32 v204, v205
	v_permlane32_swap_b32_e32 v98, v100
	v_permlane32_swap_b32_e32 v99, v101
	v_permlane32_swap_b32_e32 v102, v104
	v_permlane32_swap_b32_e32 v103, v105
	v_permlane32_swap_b32_e32 v106, v108
	v_permlane32_swap_b32_e32 v107, v109
	v_permlane32_swap_b32_e32 v110, v112
	v_permlane32_swap_b32_e32 v111, v113
	v_add_u32_e32 v202, s10, v181
	ds_read_b64_tr_b16 v[206:207], v202 offset:0
	ds_read_b64_tr_b16 v[208:209], v202 offset:0x800
	ds_read_b64_tr_b16 v[210:211], v202 offset:0x1000
	ds_read_b64_tr_b16 v[212:213], v202 offset:0x1800
	ds_read_b64_tr_b16 v[214:215], v202 offset:0x2000
	ds_read_b64_tr_b16 v[216:217], v202 offset:0x2800
	ds_read_b64_tr_b16 v[218:219], v202 offset:0x3000
	ds_read_b64_tr_b16 v[220:221], v202 offset:0x3800
	s_lshl_b32 s33, s35, 14
	s_add_i32 s36, s33, 0
	s_waitcnt vmcnt(0)
	v_add_u32_e32 v222, s36, v192
	s_cmp_ge_u32 s30, s31
	s_waitcnt vmcnt(3)
	ds_write_b128 v222, v[146:149]
	v_add_u32_e32 v222, s36, v193
	s_cselect_b64 s[8:9], -1, 0
	s_waitcnt vmcnt(2)
	ds_write_b128 v222, v[150:153]
	v_add_u32_e32 v222, s33, v195
	s_and_b64 vcc, exec, s[8:9]
	s_waitcnt vmcnt(1)
	ds_write_b128 v222, v[154:157] offset:49152
	s_waitcnt vmcnt(0)
	ds_write_b128 v222, v[158:161] offset:57344
	s_cbranch_vccnz .LBB0_324
	v_add_co_u32_e32 v146, vcc, 0xfffe0000, v166
	s_nop 1
	v_addc_co_u32_e32 v147, vcc, -1, v167, vcc
	v_add_co_u32_e32 v150, vcc, 0xfb7e0000, v166
	s_nop 1
	v_addc_co_u32_e32 v151, vcc, -1, v167, vcc
	v_add_co_u32_e32 v158, vcc, 0xfb800000, v166
	global_load_dwordx4 v[146:149], v[146:147], off
	s_nop 0
	global_load_dwordx4 v[154:157], v[150:151], off
	v_addc_co_u32_e32 v159, vcc, -1, v167, vcc
	global_load_dwordx4 v[150:153], v[166:167], off
	s_nop 0
	global_load_dwordx4 v[158:161], v[158:159], off
; #define SBAR() __builtin_amdgcn_sched_barrier(0)
; template <bool FIRST> __device__ __forceinline__ void partialSM_ps(f32x16& p0, f32x16& p1, float& m_reg, float& alpha, f32x16& negm) {
;   float pmax = p0[0];
; #pragma unroll
;   for (int r = 1; r < 16; ++r) pmax = fmaxf(pmax, p0[r]);
; #pragma unroll
;   for (int r = 0; r < 16; ++r) pmax = fmaxf(pmax, p1[r]);
;   { auto rr = __builtin_amdgcn_permlane32_swap(__float_as_uint(pmax), __float_as_uint(pmax), false, false);
;     pmax = fmaxf(__uint_as_float(rr[0]), __uint_as_float(rr[1])); }
;   alpha = 1.f;
;   if (FIRST || !__builtin_expect(__all(pmax <= THRL), 1)) {
; template <int D0> __device__ __forceinline__ void pv_one(f32x16& od, int vb, bf16x8 pa0, bf16x8 pa1, bf16x8 pa2, bf16x8 pa3) {
;   const s16x4 l0 = tr_read<v_rd_off(D0, 0, 0)>(vb), h0 = tr_read<v_rd_off(D0, 0, 1)>(vb), l1 = tr_read<v_rd_off(D0, 1, 0)>(vb), h1 = tr_read<v_rd_off(D0, 1, 1)>(vb);
;   const s16x4 l2 = tr_read<v_rd_off(D0, 2, 0)>(vb), h2 = tr_read<v_rd_off(D0, 2, 1)>(vb), l3 = tr_read<v_rd_off(D0, 3, 0)>(vb), h3 = tr_read<v_rd_off(D0, 3, 1)>(vb);
;   asm volatile("s_waitcnt lgkmcnt(0)" ::: "memory"); SBAR();
;     ...
;   od = __builtin_amdgcn_mfma_f32_32x32x16_bf16(pa0, PK(l0, h0), od, 0, 0, 0);
;   od = __builtin_amdgcn_mfma_f32_32x32x16_bf16(pa1, PK(l1, h1), od, 0, 0, 0);
;   od = __builtin_amdgcn_mfma_f32_32x32x16_bf16(pa2, PK(l2, h2), od, 0, 0, 0);
;   od = __builtin_amdgcn_mfma_f32_32x32x16_bf16(pa3, PK(l3, h3), od, 0, 0, 0);
;     ...
; }
; __device__ __forceinline__ void pv_d0(f32x16* o, int vb, bf16x8 pa0, bf16x8 pa1, bf16x8 pa2, bf16x8 pa3) {
;   pv_one<0>(o[0], vb, pa0, pa1, pa2, pa3); pv_one<1>(o[1], vb, pa0, pa1, pa2, pa3); pv_one<2>(o[2], vb, pa0, pa1, pa2, pa3); pv_one<3>(o[3], vb, pa0, pa1, pa2, pa3);
; }
.LBB0_324:
	s_waitcnt lgkmcnt(4)
	s_nop 0
	v_mfma_f32_32x32x16_bf16 v[2:17], v[98:101], v[206:209], v[2:17]
	ds_read_b64_tr_b16 v[206:207], v202 offset:0x200
	ds_read_b64_tr_b16 v[208:209], v202 offset:0xa00
	v_mfma_f32_32x32x16_bf16 v[2:17], v[102:105], v[210:213], v[2:17]
	ds_read_b64_tr_b16 v[210:211], v202 offset:0x1200
	ds_read_b64_tr_b16 v[212:213], v202 offset:0x1a00
	v_mfma_f32_32x32x16_bf16 v[2:17], v[106:109], v[214:217], v[2:17]
	ds_read_b64_tr_b16 v[214:215], v202 offset:0x2200
	ds_read_b64_tr_b16 v[216:217], v202 offset:0x2a00
	v_mfma_f32_32x32x16_bf16 v[2:17], v[110:113], v[218:221], v[2:17]
	ds_read_b64_tr_b16 v[218:219], v202 offset:0x3200
	ds_read_b64_tr_b16 v[220:221], v202 offset:0x3a00
	s_waitcnt lgkmcnt(0)
	v_mfma_f32_32x32x16_bf16 v[50:65], v[98:101], v[206:209], v[50:65]
	ds_read_b64_tr_b16 v[206:207], v202 offset:0x400
	ds_read_b64_tr_b16 v[208:209], v202 offset:0xc00
	v_mfma_f32_32x32x16_bf16 v[50:65], v[102:105], v[210:213], v[50:65]
	ds_read_b64_tr_b16 v[210:211], v202 offset:0x1400
	ds_read_b64_tr_b16 v[212:213], v202 offset:0x1c00
	v_mfma_f32_32x32x16_bf16 v[50:65], v[106:109], v[214:217], v[50:65]
	ds_read_b64_tr_b16 v[214:215], v202 offset:0x2400
	ds_read_b64_tr_b16 v[216:217], v202 offset:0x2c00
	v_mfma_f32_32x32x16_bf16 v[50:65], v[110:113], v[218:221], v[50:65]
	ds_read_b64_tr_b16 v[218:219], v202 offset:0x3400
	ds_read_b64_tr_b16 v[220:221], v202 offset:0x3c00
	s_waitcnt lgkmcnt(0)
	v_mfma_f32_32x32x16_bf16 v[34:49], v[98:101], v[206:209], v[34:49]
	ds_read_b64_tr_b16 v[206:207], v202 offset:0x600
	ds_read_b64_tr_b16 v[208:209], v202 offset:0xe00
	v_mfma_f32_32x32x16_bf16 v[34:49], v[102:105], v[210:213], v[34:49]
	ds_read_b64_tr_b16 v[210:211], v202 offset:0x1600
	ds_read_b64_tr_b16 v[212:213], v202 offset:0x1e00
	v_mfma_f32_32x32x16_bf16 v[34:49], v[106:109], v[214:217], v[34:49]
	ds_read_b64_tr_b16 v[214:215], v202 offset:0x2600
	ds_read_b64_tr_b16 v[216:217], v202 offset:0x2e00
	v_mfma_f32_32x32x16_bf16 v[34:49], v[110:113], v[218:221], v[34:49]
	ds_read_b64_tr_b16 v[218:219], v202 offset:0x3600
	ds_read_b64_tr_b16 v[220:221], v202 offset:0x3e00
	s_waitcnt lgkmcnt(0)
	v_mfma_f32_32x32x16_bf16 v[18:33], v[98:101], v[206:209], v[18:33]
	v_max_f32_e32 v98, v115, v115
	v_max_f32_e32 v99, v114, v114
	v_max_f32_e32 v98, v99, v98
	v_max3_f32 v98, v98, v116, v117
	v_max3_f32 v98, v98, v118, v119
	v_max3_f32 v98, v98, v120, v121
	v_max3_f32 v98, v98, v122, v123
	v_mfma_f32_32x32x16_bf16 v[18:33], v[102:105], v[210:213], v[18:33]
	v_max3_f32 v98, v98, v124, v125
	v_max3_f32 v98, v98, v126, v127
	v_max3_f32 v98, v98, v128, v129
	v_max3_f32 v98, v98, v82, v83
	v_max3_f32 v98, v98, v84, v85
	v_max3_f32 v98, v98, v86, v87
	v_max3_f32 v98, v98, v88, v89
	v_mfma_f32_32x32x16_bf16 v[18:33], v[106:109], v[214:217], v[18:33]
	v_max3_f32 v98, v98, v90, v91
	v_max3_f32 v98, v98, v92, v93
	v_max3_f32 v98, v98, v94, v95
	v_max3_f32 v98, v98, v96, v97
	v_mov_b32_e32 v99, v98
	s_nop 1
	v_permlane32_swap_b32_e32 v98, v99
	v_mfma_f32_32x32x16_bf16 v[18:33], v[110:113], v[218:221], v[18:33]
	v_max_f32_e32 v99, v99, v99
	v_max_f32_e32 v98, v98, v98
	v_max_f32_e32 v98, v98, v99
	v_cmp_ge_f32_e32 vcc, s0, v98
	s_cmp_eq_u64 vcc, exec
	v_mov_b32_e32 v202, 1.0
	s_cbranch_scc0 .LBB0_332
